# progwait + G3 epilogue: fold -log2e / -ln2 into gate/up row scales (drops 64 v_mul per wave-unit)
# baseline (speedup 1.0000x reference)
; __device__ __forceinline__ float ss2f(unsigned long long v) { return (float)v * (1.0f / 16777216.0f); }
; __device__ __forceinline__ u32x4 pack8(f32x4 v0, f32x4 v1) { u32x4 w; w.x = cvt_pk_bf16(v0[0], v0[1]); w.y = cvt_pk_bf16(v0[2], v0[3]); w.z = cvt_pk_bf16(v1[0], v1[1]); w.w = cvt_pk_bf16(v1[2], v1[3]); return w; }
; __device__ __forceinline__ void rstd8(float (&r)[8], const PreSS& p, int fr) {
;     const float a = __builtin_amdgcn_rsqf(ss2f(p.v0) * (1.0f / 1024.0f) + RMS_EPS), b = __builtin_amdgcn_rsqf(ss2f(p.v1) * (1.0f / 1024.0f) + RMS_EPS);
; #pragma unroll
;     for (int k = 0; k < 8; ++k) r[k] = __shfl((k & 1) ? b : a, fr + 16 * (k >> 1));
; }
; __device__ __forceinline__ float silu1(float v) { return v * __builtin_amdgcn_rcpf(1.0f + __builtin_amdgcn_exp2f(-1.4426950408889634f * v)); }
; __device__ __forceinline__ f32x4 silu4(f32x4 v) { return (f32x4){silu1(v[0]), silu1(v[1]), silu1(v[2]), silu1(v[3])}; }
;     __device__ __forceinline__ void operator()(const f32x4 (&acc)[2][2][4][2], const Unit& u, int wr, int wc, int fr, int fq, const Pre& pre) const {
;         const int row0 = u.pm * BM + wr * 64 + fr, col0 = u.pn * HALF + wc * 32 + 8 * fq;
;         float rs8[8]; rstd8(rs8, pre, fr);
; #pragma unroll
;         for (int ai = 0; ai < 2; ++ai)
; #pragma unroll
;             for (int m = 0; m < 4; ++m) { const int row = row0 + ai * HALF + m * 16; const float r = rs8[ai * 4 + m];
;                 const f32x4 g0 = silu4(acc[ai][0][m][0] * r), g1 = silu4(acc[ai][0][m][1] * r);
;                 const f32x4 v0 = g0 * (acc[ai][1][m][0] * r), v1 = g1 * (acc[ai][1][m][1] * r);
;                 *(u32x4*)(O + (size_t)row * 2816 + col0) = pack8(v0, v1); }
.LBB0_155:
	s_waitcnt vmcnt(8)
	v_ffbh_u32_e32 v143, v153
	v_min_u32_e32 v143, 32, v143
	v_lshlrev_b64 v[152:153], v143, v[152:153]
	v_min_u32_e32 v152, 1, v152
	v_or_b32_e32 v152, v153, v152
	v_cvt_f32_u32_e32 v152, v152
	v_sub_u32_e32 v143, 32, v143
	v_lshl_or_b32 v164, s4, 7, v159
	v_ashrrev_i32_e32 v165, 31, v164
	v_ldexp_f32 v143, v152, v143
	v_ffbh_u32_e32 v152, v147
	v_min_u32_e32 v152, 32, v152
	v_lshlrev_b64 v[146:147], v152, v[146:147]
	v_min_u32_e32 v146, 1, v146
	v_or_b32_e32 v146, v147, v146
	v_mul_f32_e32 v143, 0x33800000, v143
	v_cvt_f32_u32_e32 v146, v146
	v_fmamk_f32 v143, v143, 0x3a800000, v233
	v_rsq_f32_e32 v143, v143
	v_sub_u32_e32 v147, 32, v152
	v_ldexp_f32 v146, v146, v147
	v_and_or_b32 v147, v236, 64, v145
	v_lshlrev_b32_e32 v147, 2, v147
	ds_bpermute_b32 v166, v147, v143
	ds_bpermute_b32 v160, v147, v143 offset:64
	ds_bpermute_b32 v156, v147, v143 offset:128
	ds_bpermute_b32 v152, v147, v143 offset:192
	v_mul_f32_e32 v146, 0x33800000, v146
	s_waitcnt lgkmcnt(3)
	v_mul_f32_e32 v196, 0xbfb8aa3b, v166
	v_mul_f32_e32 v197, 0xbf317218, v166
	v_pk_mul_f32 v[124:125], v[124:125], v[196:197] op_sel_hi:[1,0]
	v_pk_mul_f32 v[126:127], v[126:127], v[196:197] op_sel_hi:[1,0]
	v_exp_f32_e32 v143, v124
	v_pk_mul_f32 v[120:121], v[120:121], v[196:197] op_sel_hi:[1,0]
	v_pk_mul_f32 v[122:123], v[122:123], v[196:197] op_sel_hi:[1,0]
	v_fmamk_f32 v146, v146, 0x3a800000, v233
	v_add_f32_e32 v143, 1.0, v143
	v_rcp_f32_e32 v168, v143
	v_exp_f32_e32 v143, v125
	v_rsq_f32_e32 v146, v146
	v_pk_mul_f32 v[116:117], v[116:117], v[196:197] op_sel:[0,1]
	v_pk_mul_f32 v[118:119], v[118:119], v[196:197] op_sel:[0,1]
	v_add_f32_e32 v143, 1.0, v143
	v_rcp_f32_e32 v169, v143
	v_exp_f32_e32 v143, v126
	ds_bpermute_b32 v162, v147, v146
	v_pk_mul_f32 v[124:125], v[124:125], v[168:169]
	v_pk_mul_f32 v[112:113], v[112:113], v[196:197] op_sel:[0,1]
	v_add_f32_e32 v143, 1.0, v143
	v_rcp_f32_e32 v170, v143
	v_exp_f32_e32 v143, v127
	v_pk_mul_f32 v[116:117], v[116:117], v[124:125]
	v_pk_mul_f32 v[114:115], v[114:115], v[196:197] op_sel:[0,1]
	v_cvt_pk_bf16_f32 v116, v116, v117
	v_add_f32_e32 v143, 1.0, v143
	v_rcp_f32_e32 v171, v143
	v_exp_f32_e32 v143, v120
	s_movk_i32 s4, 0x1600
	v_pk_mul_f32 v[126:127], v[126:127], v[170:171]
	s_waitcnt lgkmcnt(0)
	v_mul_f32_e32 v234, 0xbfb8aa3b, v162
	v_mul_f32_e32 v235, 0xbf317218, v162
	v_pk_mul_f32 v[110:111], v[110:111], v[234:235] op_sel_hi:[1,0]
	v_add_f32_e32 v143, 1.0, v143
	v_rcp_f32_e32 v168, v143
	v_exp_f32_e32 v143, v121
	v_pk_mul_f32 v[118:119], v[118:119], v[126:127]
	v_pk_mul_f32 v[108:109], v[108:109], v[234:235] op_sel_hi:[1,0]
	v_cvt_pk_bf16_f32 v117, v118, v119
	v_add_f32_e32 v143, 1.0, v143
	v_rcp_f32_e32 v169, v143
	v_exp_f32_e32 v143, v122
	v_pk_mul_f32 v[106:107], v[106:107], v[234:235] op_sel_hi:[1,0]
	v_pk_mul_f32 v[120:121], v[120:121], v[168:169]
	v_pk_mul_f32 v[104:105], v[104:105], v[234:235] op_sel_hi:[1,0]
	v_add_f32_e32 v143, 1.0, v143
	v_rcp_f32_e32 v170, v143
	v_exp_f32_e32 v143, v123
	v_pk_mul_f32 v[112:113], v[112:113], v[120:121]
	v_pk_mul_f32 v[100:101], v[100:101], v[234:235] op_sel:[0,1]
	v_cvt_pk_bf16_f32 v118, v112, v113
	v_add_f32_e32 v143, 1.0, v143
	v_rcp_f32_e32 v171, v143
	v_mov_b64_e32 v[112:113], s[30:31]
	v_mad_i64_i32 v[120:121], s[20:21], v142, s4, v[112:113]
	v_pk_mul_f32 v[122:123], v[122:123], v[170:171]
	v_pk_mul_f32 v[96:97], v[96:97], v[234:235] op_sel:[0,1]
	v_pk_mul_f32 v[114:115], v[114:115], v[122:123]
	v_pk_mul_f32 v[98:99], v[98:99], v[234:235] op_sel:[0,1]
	v_cvt_pk_bf16_f32 v119, v114, v115
	v_lshlrev_b64 v[114:115], 1, v[164:165]
	v_lshl_add_u64 v[120:121], v[120:121], 0, v[114:115]
	global_store_dwordx4 v[120:121], v[116:119], off nt
	v_or_b32_e32 v120, 16, v142
	v_pk_mul_f32 v[102:103], v[102:103], v[234:235] op_sel:[0,1]
	v_exp_f32_e32 v116, v108
	v_exp_f32_e32 v117, v109
	v_exp_f32_e32 v118, v110
	v_exp_f32_e32 v119, v111
	v_add_f32_e32 v116, 1.0, v116
	v_add_f32_e32 v117, 1.0, v117
	v_add_f32_e32 v118, 1.0, v118
	v_add_f32_e32 v119, 1.0, v119
	v_rcp_f32_e32 v116, v116
	v_rcp_f32_e32 v117, v117
	v_rcp_f32_e32 v118, v118
	v_rcp_f32_e32 v119, v119
	v_mul_f32_e32 v248, 0xbfb8aa3b, v160
	v_mul_f32_e32 v249, 0xbf317218, v160
	v_pk_mul_f32 v[94:95], v[94:95], v[248:249] op_sel_hi:[1,0]
	v_pk_mul_f32 v[108:109], v[108:109], v[116:117]
	v_pk_mul_f32 v[110:111], v[110:111], v[118:119]
	v_exp_f32_e32 v116, v104
	v_exp_f32_e32 v117, v105
	v_exp_f32_e32 v118, v106
	v_exp_f32_e32 v119, v107
	v_add_f32_e32 v116, 1.0, v116
	v_add_f32_e32 v117, 1.0, v117
	v_add_f32_e32 v118, 1.0, v118
	v_add_f32_e32 v119, 1.0, v119
	v_rcp_f32_e32 v116, v116
	v_rcp_f32_e32 v117, v117
	v_rcp_f32_e32 v118, v118
	v_rcp_f32_e32 v119, v119
	v_pk_mul_f32 v[100:101], v[100:101], v[108:109]
	v_pk_mul_f32 v[104:105], v[104:105], v[116:117]
	v_pk_mul_f32 v[102:103], v[102:103], v[110:111]
	v_pk_mul_f32 v[106:107], v[106:107], v[118:119]
	v_pk_mul_f32 v[92:93], v[92:93], v[248:249] op_sel_hi:[1,0]
	v_pk_mul_f32 v[106:107], v[98:99], v[106:107]
	v_pk_mul_f32 v[98:99], v[96:97], v[104:105]
	v_cvt_pk_bf16_f32 v96, v100, v101
	v_mad_i64_i32 v[100:101], s[20:21], v120, s4, v[112:113]
	v_cvt_pk_bf16_f32 v97, v102, v103
	v_cvt_pk_bf16_f32 v98, v98, v99
	v_cvt_pk_bf16_f32 v99, v106, v107
	v_lshl_add_u64 v[100:101], v[100:101], 0, v[114:115]
	global_store_dwordx4 v[100:101], v[96:99], off nt
	v_pk_mul_f32 v[90:91], v[90:91], v[248:249] op_sel_hi:[1,0]
	v_pk_mul_f32 v[88:89], v[88:89], v[248:249] op_sel_hi:[1,0]
	v_exp_f32_e32 v96, v92
	v_exp_f32_e32 v97, v93
	v_exp_f32_e32 v98, v94
	v_exp_f32_e32 v99, v95
	v_add_f32_e32 v96, 1.0, v96
	v_add_f32_e32 v97, 1.0, v97
	v_add_f32_e32 v98, 1.0, v98
	v_add_f32_e32 v99, 1.0, v99
	v_rcp_f32_e32 v96, v96
	v_rcp_f32_e32 v97, v97
	v_rcp_f32_e32 v98, v98
	v_rcp_f32_e32 v99, v99
	ds_bpermute_b32 v158, v147, v146 offset:64
	v_pk_mul_f32 v[92:93], v[92:93], v[96:97]
	v_pk_mul_f32 v[94:95], v[94:95], v[98:99]
	v_exp_f32_e32 v96, v88
	v_exp_f32_e32 v97, v89
	v_exp_f32_e32 v98, v90
	v_exp_f32_e32 v99, v91
	v_add_f32_e32 v96, 1.0, v96
	v_add_f32_e32 v97, 1.0, v97
	v_add_f32_e32 v98, 1.0, v98
	v_add_f32_e32 v99, 1.0, v99
	v_rcp_f32_e32 v96, v96
	v_rcp_f32_e32 v97, v97
	v_rcp_f32_e32 v98, v98
	v_rcp_f32_e32 v99, v99
	v_pk_mul_f32 v[84:85], v[84:85], v[248:249] op_sel:[0,1]
	v_or_b32_e32 v100, 32, v142
	v_pk_mul_f32 v[88:89], v[88:89], v[96:97]
	v_pk_mul_f32 v[90:91], v[90:91], v[98:99]
	v_pk_mul_f32 v[84:85], v[84:85], v[92:93]
	v_pk_mul_f32 v[80:81], v[80:81], v[248:249] op_sel:[0,1]
	v_pk_mul_f32 v[82:83], v[82:83], v[248:249] op_sel:[0,1]
	v_pk_mul_f32 v[86:87], v[86:87], v[248:249] op_sel:[0,1]
	v_pk_mul_f32 v[90:91], v[82:83], v[90:91]
	v_pk_mul_f32 v[82:83], v[80:81], v[88:89]
	v_cvt_pk_bf16_f32 v80, v84, v85
	v_mad_i64_i32 v[84:85], s[20:21], v100, s4, v[112:113]
	v_pk_mul_f32 v[86:87], v[86:87], v[94:95]
	v_lshl_add_u64 v[84:85], v[84:85], 0, v[114:115]
	v_cvt_pk_bf16_f32 v81, v86, v87
	v_cvt_pk_bf16_f32 v82, v82, v83
	v_cvt_pk_bf16_f32 v83, v90, v91
	s_waitcnt lgkmcnt(0)
; __device__ __forceinline__ u32x4 pack8(f32x4 v0, f32x4 v1) { u32x4 w; w.x = cvt_pk_bf16(v0[0], v0[1]); w.y = cvt_pk_bf16(v0[2], v0[3]); w.z = cvt_pk_bf16(v1[0], v1[1]); w.w = cvt_pk_bf16(v1[2], v1[3]); return w; }
; __device__ __forceinline__ float silu1(float v) { return v * __builtin_amdgcn_rcpf(1.0f + __builtin_amdgcn_exp2f(-1.4426950408889634f * v)); }
; __device__ __forceinline__ f32x4 silu4(f32x4 v) { return (f32x4){silu1(v[0]), silu1(v[1]), silu1(v[2]), silu1(v[3])}; }
;     __device__ __forceinline__ void operator()(const f32x4 (&acc)[2][2][4][2], const Unit& u, int wr, int wc, int fr, int fq, const Pre& pre) const {
;     ...
;             for (int m = 0; m < 4; ++m) { const int row = row0 + ai * HALF + m * 16; const float r = rs8[ai * 4 + m];
;                 const f32x4 g0 = silu4(acc[ai][0][m][0] * r), g1 = silu4(acc[ai][0][m][1] * r);
;                 const f32x4 v0 = g0 * (acc[ai][1][m][0] * r), v1 = g1 * (acc[ai][1][m][1] * r);
;                 *(u32x4*)(O + (size_t)row * 2816 + col0) = pack8(v0, v1); }
	v_mul_f32_e32 v250, 0xbfb8aa3b, v158
	v_mul_f32_e32 v251, 0xbf317218, v158
	v_pk_mul_f32 v[78:79], v[78:79], v[250:251] op_sel_hi:[1,0]
	v_pk_mul_f32 v[76:77], v[76:77], v[250:251] op_sel_hi:[1,0]
	global_store_dwordx4 v[84:85], v[80:83], off nt
	v_pk_mul_f32 v[74:75], v[74:75], v[250:251] op_sel_hi:[1,0]
	v_pk_mul_f32 v[72:73], v[72:73], v[250:251] op_sel_hi:[1,0]
	v_exp_f32_e32 v80, v76
	v_exp_f32_e32 v81, v77
	v_exp_f32_e32 v82, v78
	v_exp_f32_e32 v83, v79
	v_add_f32_e32 v80, 1.0, v80
	v_add_f32_e32 v81, 1.0, v81
	v_add_f32_e32 v82, 1.0, v82
	v_add_f32_e32 v83, 1.0, v83
	v_rcp_f32_e32 v80, v80
	v_rcp_f32_e32 v81, v81
	v_rcp_f32_e32 v82, v82
	v_rcp_f32_e32 v83, v83
	v_pk_mul_f32 v[68:69], v[68:69], v[250:251] op_sel:[0,1]
	v_pk_mul_f32 v[76:77], v[76:77], v[80:81]
	v_pk_mul_f32 v[78:79], v[78:79], v[82:83]
	v_exp_f32_e32 v80, v72
	v_exp_f32_e32 v81, v73
	v_exp_f32_e32 v82, v74
	v_exp_f32_e32 v83, v75
	v_add_f32_e32 v80, 1.0, v80
	v_add_f32_e32 v81, 1.0, v81
	v_add_f32_e32 v82, 1.0, v82
	v_add_f32_e32 v83, 1.0, v83
	v_rcp_f32_e32 v80, v80
	v_rcp_f32_e32 v81, v81
	v_rcp_f32_e32 v82, v82
	v_rcp_f32_e32 v83, v83
	v_or_b32_e32 v84, 48, v142
	v_pk_mul_f32 v[72:73], v[72:73], v[80:81]
	v_pk_mul_f32 v[68:69], v[68:69], v[76:77]
	v_pk_mul_f32 v[74:75], v[74:75], v[82:83]
	v_pk_mul_f32 v[64:65], v[64:65], v[250:251] op_sel:[0,1]
	v_pk_mul_f32 v[66:67], v[66:67], v[250:251] op_sel:[0,1]
	v_pk_mul_f32 v[70:71], v[70:71], v[250:251] op_sel:[0,1]
	v_pk_mul_f32 v[74:75], v[66:67], v[74:75]
	v_pk_mul_f32 v[66:67], v[64:65], v[72:73]
	v_cvt_pk_bf16_f32 v64, v68, v69
	v_mad_i64_i32 v[68:69], s[20:21], v84, s4, v[112:113]
	v_pk_mul_f32 v[70:71], v[70:71], v[78:79]
	v_lshl_add_u64 v[68:69], v[68:69], 0, v[114:115]
	v_cvt_pk_bf16_f32 v65, v70, v71
	v_cvt_pk_bf16_f32 v66, v66, v67
	v_cvt_pk_bf16_f32 v67, v74, v75
	v_mul_f32_e32 v196, 0xbfb8aa3b, v156
	v_mul_f32_e32 v197, 0xbf317218, v156
	v_pk_mul_f32 v[62:63], v[62:63], v[196:197] op_sel_hi:[1,0]
	v_pk_mul_f32 v[60:61], v[60:61], v[196:197] op_sel_hi:[1,0]
	global_store_dwordx4 v[68:69], v[64:67], off nt
	v_pk_mul_f32 v[58:59], v[58:59], v[196:197] op_sel_hi:[1,0]
	v_pk_mul_f32 v[56:57], v[56:57], v[196:197] op_sel_hi:[1,0]
	v_exp_f32_e32 v64, v60
	v_exp_f32_e32 v65, v61
	v_exp_f32_e32 v66, v62
	v_exp_f32_e32 v67, v63
	v_add_f32_e32 v64, 1.0, v64
	v_add_f32_e32 v65, 1.0, v65
	v_add_f32_e32 v66, 1.0, v66
	v_add_f32_e32 v67, 1.0, v67
	v_rcp_f32_e32 v64, v64
	v_rcp_f32_e32 v65, v65
	v_rcp_f32_e32 v66, v66
	v_rcp_f32_e32 v67, v67
	ds_bpermute_b32 v154, v147, v146 offset:128
	v_pk_mul_f32 v[60:61], v[60:61], v[64:65]
	v_pk_mul_f32 v[62:63], v[62:63], v[66:67]
	v_exp_f32_e32 v64, v56
	v_exp_f32_e32 v65, v57
	v_exp_f32_e32 v66, v58
	v_exp_f32_e32 v67, v59
	v_add_f32_e32 v64, 1.0, v64
	v_add_f32_e32 v65, 1.0, v65
	v_add_f32_e32 v66, 1.0, v66
	v_add_f32_e32 v67, 1.0, v67
	v_rcp_f32_e32 v64, v64
	v_rcp_f32_e32 v65, v65
	v_rcp_f32_e32 v66, v66
	v_rcp_f32_e32 v67, v67
	v_pk_mul_f32 v[52:53], v[52:53], v[196:197] op_sel:[0,1]
	v_add_u32_e32 v68, 0x80, v142
	v_pk_mul_f32 v[56:57], v[56:57], v[64:65]
	v_pk_mul_f32 v[58:59], v[58:59], v[66:67]
	v_pk_mul_f32 v[52:53], v[52:53], v[60:61]
	v_pk_mul_f32 v[48:49], v[48:49], v[196:197] op_sel:[0,1]
	v_pk_mul_f32 v[50:51], v[50:51], v[196:197] op_sel:[0,1]
	v_pk_mul_f32 v[54:55], v[54:55], v[196:197] op_sel:[0,1]
	v_pk_mul_f32 v[58:59], v[50:51], v[58:59]
	v_pk_mul_f32 v[50:51], v[48:49], v[56:57]
	v_cvt_pk_bf16_f32 v48, v52, v53
	v_mad_i64_i32 v[52:53], s[20:21], v68, s4, v[112:113]
	v_pk_mul_f32 v[54:55], v[54:55], v[62:63]
	v_lshl_add_u64 v[52:53], v[52:53], 0, v[114:115]
	v_cvt_pk_bf16_f32 v49, v54, v55
	v_cvt_pk_bf16_f32 v50, v50, v51
	v_cvt_pk_bf16_f32 v51, v58, v59
	s_waitcnt lgkmcnt(0)
; __device__ __forceinline__ u32x4 pack8(f32x4 v0, f32x4 v1) { u32x4 w; w.x = cvt_pk_bf16(v0[0], v0[1]); w.y = cvt_pk_bf16(v0[2], v0[3]); w.z = cvt_pk_bf16(v1[0], v1[1]); w.w = cvt_pk_bf16(v1[2], v1[3]); return w; }
; __device__ __forceinline__ float silu1(float v) { return v * __builtin_amdgcn_rcpf(1.0f + __builtin_amdgcn_exp2f(-1.4426950408889634f * v)); }
; __device__ __forceinline__ f32x4 silu4(f32x4 v) { return (f32x4){silu1(v[0]), silu1(v[1]), silu1(v[2]), silu1(v[3])}; }
;     __device__ __forceinline__ void operator()(const f32x4 (&acc)[2][2][4][2], const Unit& u, int wr, int wc, int fr, int fq, const Pre& pre) const {
;     ...
;             for (int m = 0; m < 4; ++m) { const int row = row0 + ai * HALF + m * 16; const float r = rs8[ai * 4 + m];
;                 const f32x4 g0 = silu4(acc[ai][0][m][0] * r), g1 = silu4(acc[ai][0][m][1] * r);
;                 const f32x4 v0 = g0 * (acc[ai][1][m][0] * r), v1 = g1 * (acc[ai][1][m][1] * r);
;                 *(u32x4*)(O + (size_t)row * 2816 + col0) = pack8(v0, v1); }
	v_mul_f32_e32 v234, 0xbfb8aa3b, v154
	v_mul_f32_e32 v235, 0xbf317218, v154
	v_pk_mul_f32 v[46:47], v[46:47], v[234:235] op_sel_hi:[1,0]
	v_pk_mul_f32 v[44:45], v[44:45], v[234:235] op_sel_hi:[1,0]
	global_store_dwordx4 v[52:53], v[48:51], off nt
	v_pk_mul_f32 v[42:43], v[42:43], v[234:235] op_sel_hi:[1,0]
	v_pk_mul_f32 v[40:41], v[40:41], v[234:235] op_sel_hi:[1,0]
	v_exp_f32_e32 v48, v44
	v_exp_f32_e32 v49, v45
	v_exp_f32_e32 v50, v46
	v_exp_f32_e32 v51, v47
	v_add_f32_e32 v48, 1.0, v48
	v_add_f32_e32 v49, 1.0, v49
	v_add_f32_e32 v50, 1.0, v50
	v_add_f32_e32 v51, 1.0, v51
	v_rcp_f32_e32 v48, v48
	v_rcp_f32_e32 v49, v49
	v_rcp_f32_e32 v50, v50
	v_rcp_f32_e32 v51, v51
	v_pk_mul_f32 v[36:37], v[36:37], v[234:235] op_sel:[0,1]
	v_pk_mul_f32 v[44:45], v[44:45], v[48:49]
	v_pk_mul_f32 v[46:47], v[46:47], v[50:51]
	v_exp_f32_e32 v48, v40
	v_exp_f32_e32 v49, v41
	v_exp_f32_e32 v50, v42
	v_exp_f32_e32 v51, v43
	v_add_f32_e32 v48, 1.0, v48
	v_add_f32_e32 v49, 1.0, v49
	v_add_f32_e32 v50, 1.0, v50
	v_add_f32_e32 v51, 1.0, v51
	v_rcp_f32_e32 v48, v48
	v_rcp_f32_e32 v49, v49
	v_rcp_f32_e32 v50, v50
	v_rcp_f32_e32 v51, v51
	v_add_u32_e32 v52, 0x90, v142
	v_pk_mul_f32 v[40:41], v[40:41], v[48:49]
	v_pk_mul_f32 v[36:37], v[36:37], v[44:45]
	v_pk_mul_f32 v[42:43], v[42:43], v[50:51]
	v_pk_mul_f32 v[32:33], v[32:33], v[234:235] op_sel:[0,1]
	v_pk_mul_f32 v[34:35], v[34:35], v[234:235] op_sel:[0,1]
	v_pk_mul_f32 v[38:39], v[38:39], v[234:235] op_sel:[0,1]
	v_pk_mul_f32 v[42:43], v[34:35], v[42:43]
	v_pk_mul_f32 v[34:35], v[32:33], v[40:41]
	v_cvt_pk_bf16_f32 v32, v36, v37
	v_mad_i64_i32 v[36:37], s[20:21], v52, s4, v[112:113]
	v_pk_mul_f32 v[38:39], v[38:39], v[46:47]
	v_lshl_add_u64 v[36:37], v[36:37], 0, v[114:115]
	v_cvt_pk_bf16_f32 v33, v38, v39
	v_cvt_pk_bf16_f32 v34, v34, v35
	v_cvt_pk_bf16_f32 v35, v42, v43
	v_mul_f32_e32 v248, 0xbfb8aa3b, v152
	v_mul_f32_e32 v249, 0xbf317218, v152
	v_pk_mul_f32 v[30:31], v[30:31], v[248:249] op_sel_hi:[1,0]
	v_pk_mul_f32 v[28:29], v[28:29], v[248:249] op_sel_hi:[1,0]
	global_store_dwordx4 v[36:37], v[32:35], off nt
	v_pk_mul_f32 v[26:27], v[26:27], v[248:249] op_sel_hi:[1,0]
	v_pk_mul_f32 v[24:25], v[24:25], v[248:249] op_sel_hi:[1,0]
	v_exp_f32_e32 v32, v28
	v_exp_f32_e32 v33, v29
	v_exp_f32_e32 v34, v30
	v_exp_f32_e32 v35, v31
	v_add_f32_e32 v32, 1.0, v32
	v_add_f32_e32 v33, 1.0, v33
	v_add_f32_e32 v34, 1.0, v34
	v_add_f32_e32 v35, 1.0, v35
	v_rcp_f32_e32 v32, v32
	v_rcp_f32_e32 v33, v33
	v_rcp_f32_e32 v34, v34
	v_rcp_f32_e32 v35, v35
	ds_bpermute_b32 v146, v147, v146 offset:192
	v_pk_mul_f32 v[28:29], v[28:29], v[32:33]
	v_pk_mul_f32 v[30:31], v[30:31], v[34:35]
	v_exp_f32_e32 v32, v24
	v_exp_f32_e32 v33, v25
	v_exp_f32_e32 v34, v26
	v_exp_f32_e32 v35, v27
	v_add_f32_e32 v32, 1.0, v32
	v_add_f32_e32 v33, 1.0, v33
	v_add_f32_e32 v34, 1.0, v34
	v_add_f32_e32 v35, 1.0, v35
	v_rcp_f32_e32 v32, v32
	v_rcp_f32_e32 v33, v33
	v_rcp_f32_e32 v34, v34
	v_rcp_f32_e32 v35, v35
	v_pk_mul_f32 v[20:21], v[20:21], v[248:249] op_sel:[0,1]
	v_add_u32_e32 v36, 0xa0, v142
	v_pk_mul_f32 v[24:25], v[24:25], v[32:33]
	v_pk_mul_f32 v[26:27], v[26:27], v[34:35]
	v_pk_mul_f32 v[20:21], v[20:21], v[28:29]
	v_pk_mul_f32 v[16:17], v[16:17], v[248:249] op_sel:[0,1]
	v_pk_mul_f32 v[18:19], v[18:19], v[248:249] op_sel:[0,1]
	v_pk_mul_f32 v[22:23], v[22:23], v[248:249] op_sel:[0,1]
	v_pk_mul_f32 v[26:27], v[18:19], v[26:27]
	v_pk_mul_f32 v[18:19], v[16:17], v[24:25]
	v_cvt_pk_bf16_f32 v16, v20, v21
	v_mad_i64_i32 v[20:21], s[20:21], v36, s4, v[112:113]
	v_pk_mul_f32 v[22:23], v[22:23], v[30:31]
	v_lshl_add_u64 v[20:21], v[20:21], 0, v[114:115]
	v_cvt_pk_bf16_f32 v17, v22, v23
	v_cvt_pk_bf16_f32 v18, v18, v19
	v_cvt_pk_bf16_f32 v19, v26, v27
	s_waitcnt lgkmcnt(0)
	v_mul_f32_e32 v250, 0xbfb8aa3b, v146
	v_mul_f32_e32 v251, 0xbf317218, v146
	v_pk_mul_f32 v[14:15], v[14:15], v[250:251] op_sel_hi:[1,0]
	v_pk_mul_f32 v[12:13], v[12:13], v[250:251] op_sel_hi:[1,0]
	global_store_dwordx4 v[20:21], v[16:19], off nt
	v_pk_mul_f32 v[10:11], v[10:11], v[250:251] op_sel_hi:[1,0]
	v_pk_mul_f32 v[8:9], v[8:9], v[250:251] op_sel_hi:[1,0]
	v_exp_f32_e32 v16, v12
	v_exp_f32_e32 v17, v13
	v_exp_f32_e32 v18, v14
	v_exp_f32_e32 v19, v15
	v_add_f32_e32 v16, 1.0, v16
	v_add_f32_e32 v17, 1.0, v17
	v_add_f32_e32 v18, 1.0, v18
	v_add_f32_e32 v19, 1.0, v19
	v_rcp_f32_e32 v16, v16
	v_rcp_f32_e32 v17, v17
	v_rcp_f32_e32 v18, v18
	v_rcp_f32_e32 v19, v19
	v_pk_mul_f32 v[4:5], v[4:5], v[250:251] op_sel:[0,1]
	v_pk_mul_f32 v[12:13], v[12:13], v[16:17]
	v_pk_mul_f32 v[14:15], v[14:15], v[18:19]
	v_exp_f32_e32 v16, v8
	v_exp_f32_e32 v17, v9
	v_exp_f32_e32 v18, v10
	v_exp_f32_e32 v19, v11
	v_add_f32_e32 v16, 1.0, v16
	v_add_f32_e32 v17, 1.0, v17
	v_add_f32_e32 v18, 1.0, v18
	v_add_f32_e32 v19, 1.0, v19
	v_rcp_f32_e32 v16, v16
	v_rcp_f32_e32 v17, v17
	v_rcp_f32_e32 v18, v18
	v_rcp_f32_e32 v19, v19
	v_add_u32_e32 v20, 0xb0, v142
	v_pk_mul_f32 v[8:9], v[8:9], v[16:17]
	v_pk_mul_f32 v[4:5], v[4:5], v[12:13]
	v_pk_mul_f32 v[10:11], v[10:11], v[18:19]
	v_pk_mul_f32 v[0:1], v[0:1], v[250:251] op_sel:[0,1]
	v_pk_mul_f32 v[2:3], v[2:3], v[250:251] op_sel:[0,1]
	v_pk_mul_f32 v[6:7], v[6:7], v[250:251] op_sel:[0,1]
	v_pk_mul_f32 v[10:11], v[2:3], v[10:11]
	v_pk_mul_f32 v[2:3], v[0:1], v[8:9]
	v_cvt_pk_bf16_f32 v0, v4, v5
	v_mad_i64_i32 v[4:5], s[20:21], v20, s4, v[112:113]
	v_lshl_add_u64 v[4:5], v[4:5], 0, v[114:115]
	s_mov_b64 s[26:27], -1
	s_andn2_b64 vcc, exec, s[40:41]
	v_pk_mul_f32 v[6:7], v[6:7], v[14:15]
	s_nop 0
	v_cvt_pk_bf16_f32 v1, v6, v7
	v_cvt_pk_bf16_f32 v2, v2, v3
	v_cvt_pk_bf16_f32 v3, v10, v11
	global_store_dwordx4 v[4:5], v[0:3], off nt
	s_cbranch_vccnz .LBB0_148
	s_andn2_b64 vcc, exec, s[44:45]
	s_cbranch_vccnz .LBB0_147
	s_barrier
	s_branch .LBB0_147
